# v43
# baseline (speedup 1.0000x reference)
.LBB0_39:
	s_ashr_i32 s8, s13, 31
	s_lshr_b32 s8, s8, 27
	s_add_i32 s8, s13, s8
	s_lshl_b32 s9, s8, 1
	s_and_b32 s8, s8, 0xffffe0
	s_and_b32 s10, s9, 0xffffffc0
	s_sub_i32 s8, s13, s8
	s_lshl_b32 s8, s8, 8
	v_add_u32_e32 v34, s10, v8
	v_add_u32_e32 v36, s10, v9
	v_add_u32_e32 v38, s10, v10
	v_add_u32_e32 v40, s10, v11
	v_add_u32_e32 v42, s10, v12
	v_add_u32_e32 v44, s10, v13
	v_add_u32_e32 v46, s10, v14
	v_add_u32_e32 v48, s10, v15
	s_ashr_i32 s9, s8, 31
	v_ashrrev_i32_e32 v35, 31, v34
	v_ashrrev_i32_e32 v37, 31, v36
	v_ashrrev_i32_e32 v39, 31, v38
	v_ashrrev_i32_e32 v41, 31, v40
	v_ashrrev_i32_e32 v43, 31, v42
	v_ashrrev_i32_e32 v45, 31, v44
	v_ashrrev_i32_e32 v47, 31, v46
	v_ashrrev_i32_e32 v49, 31, v48
	v_lshl_add_u64 v[50:51], s[8:9], 2, v[4:5]
	v_lshlrev_b64 v[34:35], 15, v[34:35]
	v_lshlrev_b64 v[36:37], 15, v[36:37]
	v_lshlrev_b64 v[38:39], 15, v[38:39]
	v_lshlrev_b64 v[40:41], 15, v[40:41]
	v_lshlrev_b64 v[42:43], 15, v[42:43]
	v_lshlrev_b64 v[44:45], 15, v[44:45]
	v_lshlrev_b64 v[46:47], 15, v[46:47]
	v_lshlrev_b64 v[48:49], 15, v[48:49]
	v_lshl_add_u64 v[66:67], v[50:51], 0, v[34:35]
	v_lshl_add_u64 v[68:69], v[50:51], 0, v[36:37]
	v_lshl_add_u64 v[70:71], v[50:51], 0, v[38:39]
	v_lshl_add_u64 v[72:73], v[50:51], 0, v[40:41]
	v_lshl_add_u64 v[74:75], v[50:51], 0, v[42:43]
	v_lshl_add_u64 v[76:77], v[50:51], 0, v[44:45]
	v_lshl_add_u64 v[78:79], v[50:51], 0, v[46:47]
	v_lshl_add_u64 v[80:81], v[50:51], 0, v[48:49]
	global_load_dwordx4 v[34:37], v[66:67], off
	global_load_dwordx4 v[38:41], v[68:69], off
	global_load_dwordx4 v[42:45], v[70:71], off
	global_load_dwordx4 v[46:49], v[72:73], off
	global_load_dwordx4 v[50:53], v[74:75], off
	global_load_dwordx4 v[54:57], v[76:77], off
	global_load_dwordx4 v[58:61], v[78:79], off
	global_load_dwordx4 v[62:65], v[80:81], off
	v_add_u32_e32 v68, s8, v16
	s_ashr_i32 s11, s10, 31
	v_ashrrev_i32_e32 v69, 31, v68
	v_lshl_add_u64 v[66:67], s[10:11], 1, v[6:7]
	v_lshlrev_b64 v[68:69], 12, v[68:69]
	v_lshl_add_u64 v[68:69], v[66:67], 0, v[68:69]
	v_add_u32_e32 v70, s8, v19
	v_ashrrev_i32_e32 v71, 31, v70
	v_lshlrev_b64 v[70:71], 12, v[70:71]
	v_lshl_add_u64 v[70:71], v[66:67], 0, v[70:71]
	v_add_u32_e32 v72, s8, v22
	v_add_u32_e32 v74, s8, v1
	v_ashrrev_i32_e32 v73, 31, v72
	v_ashrrev_i32_e32 v75, 31, v74
	v_lshlrev_b64 v[72:73], 12, v[72:73]
	v_lshlrev_b64 v[74:75], 12, v[74:75]
	v_lshl_add_u64 v[72:73], v[66:67], 0, v[72:73]
	v_lshl_add_u64 v[66:67], v[66:67], 0, v[74:75]
	s_waitcnt vmcnt(7)
	ds_write2_b32 v26, v34, v35 offset1:1
	ds_write2_b32 v26, v36, v37 offset0:2 offset1:3
	s_waitcnt vmcnt(6)
	ds_write2_b32 v27, v38, v39 offset1:1
	ds_write2_b32 v27, v40, v41 offset0:2 offset1:3
	s_waitcnt vmcnt(5)
	ds_write2_b32 v28, v42, v43 offset1:1
	ds_write2_b32 v28, v44, v45 offset0:2 offset1:3
	s_waitcnt vmcnt(4)
	ds_write2_b32 v29, v46, v47 offset1:1
	ds_write2_b32 v29, v48, v49 offset0:2 offset1:3
	s_waitcnt vmcnt(3)
	ds_write2_b32 v30, v50, v51 offset1:1
	ds_write2_b32 v30, v52, v53 offset0:2 offset1:3
	s_waitcnt vmcnt(2)
	ds_write2_b32 v31, v54, v55 offset1:1
	ds_write2_b32 v31, v56, v57 offset0:2 offset1:3
	s_waitcnt vmcnt(1)
	ds_write2_b32 v32, v58, v59 offset1:1
	ds_write2_b32 v32, v60, v61 offset0:2 offset1:3
	s_waitcnt vmcnt(0)
	ds_write2_b32 v33, v62, v63 offset1:1
	ds_write2_b32 v33, v64, v65 offset0:2 offset1:3
	s_waitcnt lgkmcnt(0)
	s_barrier
	ds_read_b32 v34, v17 offset:1028
	ds_read_b32 v35, v17 offset:2056
	ds_read_b32 v37, v18 offset:7196
	ds_read_b32 v36, v18 offset:5140
	ds_read_b32 v38, v17 offset:3084
	ds_read_b32 v39, v17
	ds_read_b32 v40, v18 offset:4112
	ds_read_b32 v41, v18 offset:6168
	s_waitcnt lgkmcnt(2)
	s_nop 0
	v_cvt_pk_bf16_f32 v34, v39, v34
	s_nop 0
	v_cvt_pk_bf16_f32 v35, v35, v38
	s_waitcnt lgkmcnt(1)
	s_nop 0
	v_cvt_pk_bf16_f32 v36, v40, v36
	s_waitcnt lgkmcnt(0)
	s_nop 0
	v_cvt_pk_bf16_f32 v37, v41, v37
	ds_read_b32 v38, v20 offset:1028
	ds_read_b32 v39, v20 offset:2056
	ds_read_b32 v40, v21 offset:7196
	ds_read_b32 v41, v21 offset:5140
	ds_read_b32 v42, v20 offset:3084
	ds_read_b32 v43, v20
	ds_read_b32 v44, v21 offset:4112
	ds_read_b32 v45, v21 offset:6168
	global_store_dwordx4 v[68:69], v[34:37], off
	s_waitcnt lgkmcnt(2)
	s_nop 0
	s_nop 0
	v_cvt_pk_bf16_f32 v34, v43, v38
	s_nop 0
	v_cvt_pk_bf16_f32 v35, v39, v42
	s_waitcnt lgkmcnt(1)
	s_nop 0
	v_cvt_pk_bf16_f32 v36, v44, v41
	s_waitcnt lgkmcnt(0)
	s_nop 0
	v_cvt_pk_bf16_f32 v37, v45, v40
	ds_read_b32 v38, v23 offset:1028
	ds_read_b32 v39, v23 offset:2056
	ds_read_b32 v40, v24 offset:7196
	ds_read_b32 v41, v24 offset:5140
	ds_read_b32 v42, v23 offset:3084
	ds_read_b32 v43, v23
	ds_read_b32 v44, v24 offset:4112
	ds_read_b32 v45, v24 offset:6168
	global_store_dwordx4 v[70:71], v[34:37], off
	s_waitcnt lgkmcnt(2)
	s_nop 0
	s_nop 0
	v_cvt_pk_bf16_f32 v34, v43, v38
	s_nop 0
	v_cvt_pk_bf16_f32 v35, v39, v42
	s_waitcnt lgkmcnt(1)
	s_nop 0
	v_cvt_pk_bf16_f32 v36, v44, v41
	s_waitcnt lgkmcnt(0)
	s_nop 0
	v_cvt_pk_bf16_f32 v37, v45, v40
	ds_read_b32 v38, v2 offset:1028
	ds_read_b32 v39, v2 offset:2056
	ds_read_b32 v40, v25 offset:7196
	ds_read_b32 v41, v25 offset:5140
	ds_read_b32 v42, v2 offset:3084
	ds_read_b32 v43, v2
	ds_read_b32 v44, v25 offset:4112
	ds_read_b32 v45, v25 offset:6168
	global_store_dwordx4 v[72:73], v[34:37], off
	s_waitcnt lgkmcnt(2)
	s_nop 0
	s_nop 0
	v_cvt_pk_bf16_f32 v34, v43, v38
	s_nop 0
	v_cvt_pk_bf16_f32 v35, v39, v42
	s_waitcnt lgkmcnt(1)
	s_nop 0
	v_cvt_pk_bf16_f32 v36, v44, v41
	s_waitcnt lgkmcnt(0)
	s_nop 0
	v_cvt_pk_bf16_f32 v37, v45, v40
	global_store_dwordx4 v[66:67], v[34:37], off
	s_barrier
	s_addk_i32 s13, 0x100
	s_cmpk_lt_i32 s13, 0x400
	s_cbranch_scc1 .LBB0_39

.LBB0_42:
	s_ashr_i32 s6, s10, 31
	s_lshr_b32 s6, s6, 29
	s_add_i32 s6, s10, s6
	s_lshl_b32 s7, s6, 3
	s_and_b32 s6, s6, 0xfffff8
	s_and_b32 s8, s7, 0xffffffc0
	s_sub_i32 s6, s10, s6
	s_lshl_b32 s6, s6, 8
	v_add_u32_e32 v34, s8, v8
	v_add_u32_e32 v36, s8, v9
	v_add_u32_e32 v38, s8, v10
	v_add_u32_e32 v40, s8, v11
	v_add_u32_e32 v42, s8, v12
	v_add_u32_e32 v44, s8, v13
	v_add_u32_e32 v46, s8, v14
	v_add_u32_e32 v48, s8, v15
	s_ashr_i32 s7, s6, 31
	v_ashrrev_i32_e32 v35, 31, v34
	v_ashrrev_i32_e32 v37, 31, v36
	v_ashrrev_i32_e32 v39, 31, v38
	v_ashrrev_i32_e32 v41, 31, v40
	v_ashrrev_i32_e32 v43, 31, v42
	v_ashrrev_i32_e32 v45, 31, v44
	v_ashrrev_i32_e32 v47, 31, v46
	v_ashrrev_i32_e32 v49, 31, v48
	v_lshl_add_u64 v[50:51], s[6:7], 2, v[4:5]
	v_lshlrev_b64 v[34:35], 13, v[34:35]
	v_lshlrev_b64 v[36:37], 13, v[36:37]
	v_lshlrev_b64 v[38:39], 13, v[38:39]
	v_lshlrev_b64 v[40:41], 13, v[40:41]
	v_lshlrev_b64 v[42:43], 13, v[42:43]
	v_lshlrev_b64 v[44:45], 13, v[44:45]
	v_lshlrev_b64 v[46:47], 13, v[46:47]
	v_lshlrev_b64 v[48:49], 13, v[48:49]
	v_lshl_add_u64 v[66:67], v[50:51], 0, v[34:35]
	v_lshl_add_u64 v[68:69], v[50:51], 0, v[36:37]
	v_lshl_add_u64 v[70:71], v[50:51], 0, v[38:39]
	v_lshl_add_u64 v[72:73], v[50:51], 0, v[40:41]
	v_lshl_add_u64 v[74:75], v[50:51], 0, v[42:43]
	v_lshl_add_u64 v[76:77], v[50:51], 0, v[44:45]
	v_lshl_add_u64 v[78:79], v[50:51], 0, v[46:47]
	v_lshl_add_u64 v[80:81], v[50:51], 0, v[48:49]
	global_load_dwordx4 v[34:37], v[66:67], off
	global_load_dwordx4 v[38:41], v[68:69], off
	global_load_dwordx4 v[42:45], v[70:71], off
	global_load_dwordx4 v[46:49], v[72:73], off
	global_load_dwordx4 v[50:53], v[74:75], off
	global_load_dwordx4 v[54:57], v[76:77], off
	global_load_dwordx4 v[58:61], v[78:79], off
	global_load_dwordx4 v[62:65], v[80:81], off
	v_add_u32_e32 v68, s6, v16
	s_ashr_i32 s9, s8, 31
	v_ashrrev_i32_e32 v69, 31, v68
	v_lshl_add_u64 v[66:67], s[8:9], 1, v[6:7]
	v_lshlrev_b64 v[68:69], 14, v[68:69]
	v_lshl_add_u64 v[68:69], v[66:67], 0, v[68:69]
	v_add_u32_e32 v70, s6, v19
	v_ashrrev_i32_e32 v71, 31, v70
	v_lshlrev_b64 v[70:71], 14, v[70:71]
	v_lshl_add_u64 v[70:71], v[66:67], 0, v[70:71]
	v_add_u32_e32 v72, s6, v22
	v_add_u32_e32 v74, s6, v1
	v_ashrrev_i32_e32 v73, 31, v72
	v_ashrrev_i32_e32 v75, 31, v74
	v_lshlrev_b64 v[72:73], 14, v[72:73]
	v_lshlrev_b64 v[74:75], 14, v[74:75]
	v_lshl_add_u64 v[72:73], v[66:67], 0, v[72:73]
	v_lshl_add_u64 v[66:67], v[66:67], 0, v[74:75]
	s_waitcnt vmcnt(7)
	ds_write2_b32 v26, v34, v35 offset1:1
	ds_write2_b32 v26, v36, v37 offset0:2 offset1:3
	s_waitcnt vmcnt(6)
	ds_write2_b32 v27, v38, v39 offset1:1
	ds_write2_b32 v27, v40, v41 offset0:2 offset1:3
	s_waitcnt vmcnt(5)
	ds_write2_b32 v28, v42, v43 offset1:1
	ds_write2_b32 v28, v44, v45 offset0:2 offset1:3
	s_waitcnt vmcnt(4)
	ds_write2_b32 v29, v46, v47 offset1:1
	ds_write2_b32 v29, v48, v49 offset0:2 offset1:3
	s_waitcnt vmcnt(3)
	ds_write2_b32 v30, v50, v51 offset1:1
	ds_write2_b32 v30, v52, v53 offset0:2 offset1:3
	s_waitcnt vmcnt(2)
	ds_write2_b32 v31, v54, v55 offset1:1
	ds_write2_b32 v31, v56, v57 offset0:2 offset1:3
	s_waitcnt vmcnt(1)
	ds_write2_b32 v32, v58, v59 offset1:1
	ds_write2_b32 v32, v60, v61 offset0:2 offset1:3
	s_waitcnt vmcnt(0)
	ds_write2_b32 v33, v62, v63 offset1:1
	ds_write2_b32 v33, v64, v65 offset0:2 offset1:3
	s_waitcnt lgkmcnt(0)
	s_barrier
	ds_read_b32 v34, v17 offset:1028
	ds_read_b32 v35, v17 offset:2056
	ds_read_b32 v37, v18 offset:7196
	ds_read_b32 v36, v18 offset:5140
	ds_read_b32 v38, v17 offset:3084
	ds_read_b32 v39, v17
	ds_read_b32 v40, v18 offset:4112
	ds_read_b32 v41, v18 offset:6168
	s_waitcnt lgkmcnt(2)
	s_nop 0
	v_cvt_pk_bf16_f32 v34, v39, v34
	s_nop 0
	v_cvt_pk_bf16_f32 v35, v35, v38
	s_waitcnt lgkmcnt(1)
	s_nop 0
	v_cvt_pk_bf16_f32 v36, v40, v36
	s_waitcnt lgkmcnt(0)
	s_nop 0
	v_cvt_pk_bf16_f32 v37, v41, v37
	ds_read_b32 v38, v20 offset:1028
	ds_read_b32 v39, v20 offset:2056
	ds_read_b32 v40, v21 offset:7196
	ds_read_b32 v41, v21 offset:5140
	ds_read_b32 v42, v20 offset:3084
	ds_read_b32 v43, v20
	ds_read_b32 v44, v21 offset:4112
	ds_read_b32 v45, v21 offset:6168
	global_store_dwordx4 v[68:69], v[34:37], off
	s_waitcnt lgkmcnt(2)
	s_nop 0
	s_nop 0
	v_cvt_pk_bf16_f32 v34, v43, v38
	s_nop 0
	v_cvt_pk_bf16_f32 v35, v39, v42
	s_waitcnt lgkmcnt(1)
	s_nop 0
	v_cvt_pk_bf16_f32 v36, v44, v41
	s_waitcnt lgkmcnt(0)
	s_nop 0
	v_cvt_pk_bf16_f32 v37, v45, v40
	ds_read_b32 v38, v23 offset:1028
	ds_read_b32 v39, v23 offset:2056
	ds_read_b32 v40, v24 offset:7196
	ds_read_b32 v41, v24 offset:5140
	ds_read_b32 v42, v23 offset:3084
	ds_read_b32 v43, v23
	ds_read_b32 v44, v24 offset:4112
	ds_read_b32 v45, v24 offset:6168
	global_store_dwordx4 v[70:71], v[34:37], off
	s_waitcnt lgkmcnt(2)
	s_nop 0
	s_nop 0
	v_cvt_pk_bf16_f32 v34, v43, v38
	s_nop 0
	v_cvt_pk_bf16_f32 v35, v39, v42
	s_waitcnt lgkmcnt(1)
	s_nop 0
	v_cvt_pk_bf16_f32 v36, v44, v41
	s_waitcnt lgkmcnt(0)
	s_nop 0
	v_cvt_pk_bf16_f32 v37, v45, v40
	ds_read_b32 v38, v2 offset:1028
	ds_read_b32 v39, v2 offset:2056
	ds_read_b32 v40, v25 offset:7196
	ds_read_b32 v41, v25 offset:5140
	ds_read_b32 v42, v2 offset:3084
	ds_read_b32 v43, v2
	ds_read_b32 v44, v25 offset:4112
	ds_read_b32 v45, v25 offset:6168
	global_store_dwordx4 v[72:73], v[34:37], off
	s_waitcnt lgkmcnt(2)
	s_nop 0
	s_nop 0
	v_cvt_pk_bf16_f32 v34, v43, v38
	s_nop 0
	v_cvt_pk_bf16_f32 v35, v39, v42
	s_waitcnt lgkmcnt(1)
	s_nop 0
	v_cvt_pk_bf16_f32 v36, v44, v41
	s_waitcnt lgkmcnt(0)
	s_nop 0
	v_cvt_pk_bf16_f32 v37, v45, v40
	global_store_dwordx4 v[66:67], v[34:37], off
	s_barrier
	s_addk_i32 s10, 0x100
	s_cmpk_lt_i32 s10, 0x400
	s_cbranch_scc1 .LBB0_42
	s_branch .LBB0_36
